# EpiResidNorm epilogues (out-proj, FFN-down): the 32 residual-tile loads issued 16 deep with counted vmcnt instead of 2 at a time; MLA K/V fragment prefetch; code padded to baseline addresses
# baseline (speedup 1.0000x reference)
.LBB0_1000:
	s_lshl_b32 s0, s4, 5
	s_lshl_b32 s5, s53, 8
	s_lshl_b32 s1, s8, 8
	s_add_i32 s2, s5, s36
	s_or_b32 s0, s1, s0
	s_cmp_gt_i32 s53, 15
	v_lshl_or_b32 v162, v152, 3, s0
	s_cselect_b32 s0, 0x3000, 0
	s_lshl_b32 s12, s0, 2
	v_readlane_b32 s0, v255, 2
	v_readlane_b32 s1, v255, 3
	s_add_u32 s0, s0, s12
	v_ashrrev_i32_e32 v163, 31, v162
	s_addc_u32 s1, s1, 0
	v_lshlrev_b64 v[146:147], 2, v[162:163]
	v_lshl_add_u64 v[130:131], s[0:1], 0, v[146:147]
	s_movk_i32 s0, 0x4000
	v_or_b32_e32 v148, s2, v148
	v_lshl_add_u64 v[134:135], v[130:131], 0, s[26:27]
	v_add_co_u32_e32 v130, vcc, s0, v130
	v_ashrrev_i32_e32 v149, 31, v148
	v_readlane_b32 s0, v254, 61
	v_lshlrev_b64 v[150:151], 13, v[148:149]
	v_readlane_b32 s1, v254, 62
	v_addc_co_u32_e32 v131, vcc, 0, v131, vcc
	s_nop 0
	v_lshl_add_u64 v[150:151], s[0:1], 0, v[150:151]
	v_lshl_add_u64 v[150:151], v[150:151], 0, v[146:147]
	s_waitcnt vmcnt(0)
	s_barrier
	global_load_dwordx4 v[142:145], v[130:131], off
	global_load_dwordx4 v[138:141], v[134:135], off offset:16
	s_nop 0
	global_load_dwordx4 v[130:133], v[134:135], off offset:528
	s_nop 0
	global_load_dwordx4 v[134:137], v[134:135], off offset:512
	s_nop 0
	global_load_dwordx4 v[178:181], v[150:151], off offset:16
	global_load_dwordx4 v[182:185], v[150:151], off
	global_load_dwordx4 v[186:189], v[150:151], off offset:528
	global_load_dwordx4 v[190:193], v[150:151], off offset:512
	v_add_co_u32_e32 v164, vcc, 0x20000, v150
	s_nop 1
	v_addc_co_u32_e32 v165, vcc, 0, v151, vcc
	global_load_dwordx4 v[198:201], v[164:165], off offset:16
	global_load_dwordx4 v[202:205], v[164:165], off
	global_load_dwordx4 v[206:209], v[164:165], off offset:528
	global_load_dwordx4 v[214:217], v[164:165], off offset:512
	v_add_co_u32_e32 v164, vcc, 0x40000, v150
	s_nop 1
	v_addc_co_u32_e32 v165, vcc, 0, v151, vcc
	global_load_dwordx4 v[218:221], v[164:165], off offset:16
	global_load_dwordx4 v[222:225], v[164:165], off
	global_load_dwordx4 v[226:229], v[164:165], off offset:528
	global_load_dwordx4 v[230:233], v[164:165], off offset:512
	v_add_co_u32_e32 v164, vcc, 0x60000, v150
	s_nop 1
	v_addc_co_u32_e32 v165, vcc, 0, v151, vcc
	global_load_dwordx4 v[234:237], v[164:165], off offset:16
	global_load_dwordx4 v[238:241], v[164:165], off
	global_load_dwordx4 v[242:245], v[164:165], off offset:528
	global_load_dwordx4 v[154:157], v[164:165], off offset:512
	s_waitcnt vmcnt(15)
	v_pk_fma_f32 v[108:109], v[108:109], v[140:141], v[180:181]
	v_pk_fma_f32 v[106:107], v[106:107], v[138:139], v[178:179]
	v_add_co_u32_e32 v164, vcc, 0x100000, v150
	s_nop 1
	v_addc_co_u32_e32 v165, vcc, 0, v151, vcc
	global_load_dwordx4 v[178:181], v[164:165], off
	s_waitcnt vmcnt(15)
	v_pk_fma_f32 v[112:113], v[112:113], v[144:145], v[184:185]
	v_pk_fma_f32 v[110:111], v[110:111], v[142:143], v[182:183]
	global_load_dwordx4 v[182:185], v[164:165], off offset:16
	s_waitcnt vmcnt(15)
	v_pk_fma_f32 v[0:1], v[0:1], v[130:131], v[186:187]
	v_pk_fma_f32 v[2:3], v[2:3], v[132:133], v[188:189]
	global_load_dwordx4 v[186:189], v[164:165], off offset:528
	s_waitcnt vmcnt(15)
	v_pk_fma_f32 v[6:7], v[6:7], v[136:137], v[192:193]
	v_pk_fma_f32 v[4:5], v[4:5], v[134:135], v[190:191]
	global_load_dwordx4 v[190:193], v[164:165], off offset:512
	s_waitcnt vmcnt(15)
	v_pk_fma_f32 v[116:117], v[116:117], v[140:141], v[200:201]
	v_pk_fma_f32 v[114:115], v[114:115], v[138:139], v[198:199]
	v_add_co_u32_e32 v164, vcc, 0x120000, v150
	s_nop 1
	v_addc_co_u32_e32 v165, vcc, 0, v151, vcc
	global_load_dwordx4 v[198:201], v[164:165], off
	s_waitcnt vmcnt(15)
	v_pk_fma_f32 v[120:121], v[120:121], v[144:145], v[204:205]
	v_pk_fma_f32 v[118:119], v[118:119], v[142:143], v[202:203]
	global_load_dwordx4 v[202:205], v[164:165], off offset:16
	s_waitcnt vmcnt(15)
	v_pk_fma_f32 v[8:9], v[8:9], v[130:131], v[206:207]
	v_pk_fma_f32 v[10:11], v[10:11], v[132:133], v[208:209]
	global_load_dwordx4 v[206:209], v[164:165], off offset:528
	s_waitcnt vmcnt(15)
	v_pk_fma_f32 v[14:15], v[14:15], v[136:137], v[216:217]
	v_pk_fma_f32 v[12:13], v[12:13], v[134:135], v[214:215]
	global_load_dwordx4 v[214:217], v[164:165], off offset:512
	s_waitcnt vmcnt(15)
	v_pk_fma_f32 v[124:125], v[124:125], v[140:141], v[220:221]
	v_pk_fma_f32 v[122:123], v[122:123], v[138:139], v[218:219]
	v_add_co_u32_e32 v164, vcc, 0x140000, v150
	s_nop 1
	v_addc_co_u32_e32 v165, vcc, 0, v151, vcc
	global_load_dwordx4 v[218:221], v[164:165], off
	s_waitcnt vmcnt(15)
	v_pk_fma_f32 v[128:129], v[128:129], v[144:145], v[224:225]
	v_pk_fma_f32 v[126:127], v[126:127], v[142:143], v[222:223]
	global_load_dwordx4 v[222:225], v[164:165], off offset:16
	s_waitcnt vmcnt(15)
	v_pk_fma_f32 v[20:21], v[20:21], v[130:131], v[226:227]
	v_pk_fma_f32 v[22:23], v[22:23], v[132:133], v[228:229]
	global_load_dwordx4 v[226:229], v[164:165], off offset:528
	s_waitcnt vmcnt(15)
	v_pk_fma_f32 v[26:27], v[26:27], v[136:137], v[232:233]
	v_pk_fma_f32 v[24:25], v[24:25], v[134:135], v[230:231]
	global_load_dwordx4 v[230:233], v[164:165], off offset:512
	s_waitcnt vmcnt(15)
	v_pk_fma_f32 v[90:91], v[90:91], v[140:141], v[236:237]
	v_pk_fma_f32 v[88:89], v[88:89], v[138:139], v[234:235]
	v_add_co_u32_e32 v164, vcc, 0x160000, v150
	s_nop 1
	v_addc_co_u32_e32 v165, vcc, 0, v151, vcc
	global_load_dwordx4 v[234:237], v[164:165], off
	s_waitcnt vmcnt(15)
	v_pk_fma_f32 v[94:95], v[94:95], v[144:145], v[240:241]
	v_pk_fma_f32 v[92:93], v[92:93], v[142:143], v[238:239]
	global_load_dwordx4 v[238:241], v[164:165], off offset:16
	s_waitcnt vmcnt(15)
	v_pk_fma_f32 v[34:35], v[34:35], v[132:133], v[244:245]
	v_pk_fma_f32 v[32:33], v[32:33], v[130:131], v[242:243]
	global_load_dwordx4 v[242:245], v[164:165], off offset:528
	s_waitcnt vmcnt(15)
	v_pk_fma_f32 v[42:43], v[42:43], v[136:137], v[156:157]
	v_pk_fma_f32 v[40:41], v[40:41], v[134:135], v[154:155]
	global_load_dwordx4 v[154:157], v[164:165], off offset:512
	s_waitcnt vmcnt(15)
	v_pk_fma_f32 v[104:105], v[104:105], v[144:145], v[180:181]
	v_pk_fma_f32 v[102:103], v[102:103], v[142:143], v[178:179]
	s_waitcnt vmcnt(14)
	v_pk_fma_f32 v[100:101], v[100:101], v[140:141], v[184:185]
	v_pk_fma_f32 v[98:99], v[98:99], v[138:139], v[182:183]
	s_waitcnt vmcnt(13)
	v_pk_fma_f32 v[56:57], v[56:57], v[130:131], v[186:187]
	v_pk_fma_f32 v[58:59], v[58:59], v[132:133], v[188:189]
	s_waitcnt vmcnt(12)
	v_pk_fma_f32 v[62:63], v[62:63], v[136:137], v[192:193]
	v_pk_fma_f32 v[60:61], v[60:61], v[134:135], v[190:191]
	s_waitcnt vmcnt(11)
	v_pk_fma_f32 v[86:87], v[86:87], v[144:145], v[200:201]
	v_pk_fma_f32 v[84:85], v[84:85], v[142:143], v[198:199]
	s_waitcnt vmcnt(10)
	v_pk_fma_f32 v[82:83], v[82:83], v[140:141], v[204:205]
	v_pk_fma_f32 v[80:81], v[80:81], v[138:139], v[202:203]
	s_waitcnt vmcnt(9)
	v_pk_fma_f32 v[72:73], v[72:73], v[130:131], v[206:207]
	v_pk_fma_f32 v[74:75], v[74:75], v[132:133], v[208:209]
	s_waitcnt vmcnt(8)
	v_pk_fma_f32 v[78:79], v[78:79], v[136:137], v[216:217]
	v_pk_fma_f32 v[76:77], v[76:77], v[134:135], v[214:215]
	s_waitcnt vmcnt(7)
	v_pk_fma_f32 v[70:71], v[70:71], v[144:145], v[220:221]
	v_pk_fma_f32 v[68:69], v[68:69], v[142:143], v[218:219]
	s_waitcnt vmcnt(6)
	v_pk_fma_f32 v[66:67], v[66:67], v[140:141], v[224:225]
	v_pk_fma_f32 v[64:65], v[64:65], v[138:139], v[222:223]
	s_waitcnt vmcnt(5)
	v_pk_fma_f32 v[50:51], v[50:51], v[132:133], v[228:229]
	v_pk_fma_f32 v[48:49], v[48:49], v[130:131], v[226:227]
	s_waitcnt vmcnt(4)
	v_pk_fma_f32 v[54:55], v[54:55], v[136:137], v[232:233]
	v_pk_fma_f32 v[52:53], v[52:53], v[134:135], v[230:231]
	s_waitcnt vmcnt(3)
	v_pk_fma_f32 v[46:47], v[46:47], v[144:145], v[236:237]
	v_pk_fma_f32 v[44:45], v[44:45], v[142:143], v[234:235]
	s_waitcnt vmcnt(2)
	v_pk_fma_f32 v[38:39], v[38:39], v[140:141], v[240:241]
	v_pk_fma_f32 v[36:37], v[36:37], v[138:139], v[238:239]
	s_waitcnt vmcnt(1)
	v_pk_fma_f32 v[18:19], v[18:19], v[132:133], v[244:245]
	v_pk_fma_f32 v[16:17], v[16:17], v[130:131], v[242:243]
	s_waitcnt vmcnt(0)
	v_pk_fma_f32 v[28:29], v[28:29], v[134:135], v[154:155]
	v_pk_fma_f32 v[30:31], v[30:31], v[136:137], v[156:157]
	s_mov_b64 s[0:1], 0x160000
	s_branch .Lmy_pad_1
	s_nop 0
	s_nop 0
	s_nop 0
	s_nop 0
	s_nop 0
	s_nop 0
	s_nop 0
	s_nop 0
	s_nop 0
	s_nop 0
	s_nop 0
	s_nop 0
	s_nop 0
	s_nop 0
	s_nop 0
	s_nop 0
	s_nop 0
	s_nop 0
	s_nop 0
	s_nop 0
	s_nop 0
	s_nop 0
	s_nop 0
	s_nop 0
	s_nop 0
	s_nop 0
	s_nop 0
	s_nop 0
	s_nop 0
	s_nop 0
.Lmy_pad_1:
	s_lshl_b32 s0, s4, 2
	s_add_i32 s0, s0, 0
	v_cmp_eq_u32_e32 vcc, 0, v152
	v_mul_f32_e32 v132, v111, v111
	v_mul_f32_e32 v133, v113, v113
	v_fmac_f32_e32 v132, v110, v110
	v_fmac_f32_e32 v133, v112, v112
	v_add_f32_e32 v132, v132, v133
	v_mul_f32_e32 v133, v107, v107
	v_mul_f32_e32 v134, v109, v109
	v_fmac_f32_e32 v133, v106, v106
	v_fmac_f32_e32 v134, v108, v108
	v_add_f32_e32 v133, v133, v134
	v_add_f32_e32 v132, v132, v133
	v_mul_f32_e32 v133, v5, v5
	v_mul_f32_e32 v134, v7, v7
	v_fmac_f32_e32 v133, v4, v4
	v_fmac_f32_e32 v134, v6, v6
	v_add_f32_e32 v133, v133, v134
	v_add_f32_e32 v132, v133, v132
	v_mul_f32_e32 v133, v1, v1
	v_mul_f32_e32 v134, v3, v3
	v_fmac_f32_e32 v133, v0, v0
	v_fmac_f32_e32 v134, v2, v2
	v_mbcnt_lo_u32_b32 v96, -1, 0
	v_mbcnt_hi_u32_b32 v96, -1, v96
	v_add_f32_e32 v133, v133, v134
	v_lshlrev_b32_e32 v130, 2, v96
	v_xor_b32_e32 v131, 64, v130
	v_add_f32_e32 v132, v133, v132
	ds_bpermute_b32 v133, v131, v132
	v_xor_b32_e32 v130, 0x80, v130
	s_waitcnt lgkmcnt(0)
	v_add_f32_e32 v133, v132, v133
	ds_bpermute_b32 v134, v130, v133
	v_lshl_add_u32 v132, v172, 4, s0
	s_and_saveexec_b64 s[0:1], vcc
	s_cbranch_execz .LBB0_1002
	s_waitcnt lgkmcnt(0)
	v_add_f32_e32 v133, v133, v134
	ds_write_b32 v132, v133

.LBB0_1364:
	s_lshl_b32 s0, s4, 5
	s_lshl_b32 s5, s51, 8
	s_lshl_b32 s1, s8, 8
	s_add_i32 s2, s5, s36
	s_or_b32 s0, s1, s0
	s_cmp_gt_i32 s51, 15
	v_lshl_or_b32 v162, v152, 3, s0
	s_cselect_b32 s0, 0x3000, 0
	v_or_b32_e32 v148, s2, v148
	s_lshl_b32 s12, s0, 2
	v_ashrrev_i32_e32 v149, 31, v148
	s_add_u32 s0, s49, s12
	v_ashrrev_i32_e32 v163, 31, v162
	v_lshlrev_b64 v[150:151], 13, v[148:149]
	s_addc_u32 s1, s50, 0
	v_lshlrev_b64 v[146:147], 2, v[162:163]
	v_lshl_add_u64 v[150:151], s[96:97], 0, v[150:151]
	v_lshl_add_u64 v[134:135], s[0:1], 0, v[146:147]
	v_lshl_add_u64 v[150:151], v[150:151], 0, v[146:147]
	s_waitcnt vmcnt(0)
	s_barrier
	global_load_dwordx4 v[138:141], v[134:135], off offset:16
	global_load_dwordx4 v[142:145], v[134:135], off
	global_load_dwordx4 v[130:133], v[134:135], off offset:528
	s_nop 0
	global_load_dwordx4 v[134:137], v[134:135], off offset:512
	s_nop 0
	global_load_dwordx4 v[178:181], v[150:151], off offset:16
	global_load_dwordx4 v[182:185], v[150:151], off
	global_load_dwordx4 v[186:189], v[150:151], off offset:528
	global_load_dwordx4 v[190:193], v[150:151], off offset:512
	v_add_co_u32_e32 v164, vcc, 0x20000, v150
	s_nop 1
	v_addc_co_u32_e32 v165, vcc, 0, v151, vcc
	global_load_dwordx4 v[198:201], v[164:165], off offset:16
	global_load_dwordx4 v[202:205], v[164:165], off
	global_load_dwordx4 v[206:209], v[164:165], off offset:528
	global_load_dwordx4 v[214:217], v[164:165], off offset:512
	v_add_co_u32_e32 v164, vcc, 0x40000, v150
	s_nop 1
	v_addc_co_u32_e32 v165, vcc, 0, v151, vcc
	global_load_dwordx4 v[218:221], v[164:165], off offset:16
	global_load_dwordx4 v[222:225], v[164:165], off
	global_load_dwordx4 v[226:229], v[164:165], off offset:528
	global_load_dwordx4 v[230:233], v[164:165], off offset:512
	v_add_co_u32_e32 v164, vcc, 0x60000, v150
	s_nop 1
	v_addc_co_u32_e32 v165, vcc, 0, v151, vcc
	global_load_dwordx4 v[234:237], v[164:165], off offset:16
	global_load_dwordx4 v[238:241], v[164:165], off
	global_load_dwordx4 v[242:245], v[164:165], off offset:528
	global_load_dwordx4 v[154:157], v[164:165], off offset:512
	s_waitcnt vmcnt(15)
	v_pk_fma_f32 v[108:109], v[108:109], v[140:141], v[180:181]
	v_pk_fma_f32 v[106:107], v[106:107], v[138:139], v[178:179]
	v_add_co_u32_e32 v164, vcc, 0x100000, v150
	s_nop 1
	v_addc_co_u32_e32 v165, vcc, 0, v151, vcc
	global_load_dwordx4 v[178:181], v[164:165], off
	s_waitcnt vmcnt(15)
	v_pk_fma_f32 v[112:113], v[112:113], v[144:145], v[184:185]
	v_pk_fma_f32 v[110:111], v[110:111], v[142:143], v[182:183]
	global_load_dwordx4 v[182:185], v[164:165], off offset:16
	s_waitcnt vmcnt(15)
	v_pk_fma_f32 v[0:1], v[0:1], v[130:131], v[186:187]
	v_pk_fma_f32 v[2:3], v[2:3], v[132:133], v[188:189]
	global_load_dwordx4 v[186:189], v[164:165], off offset:528
	s_waitcnt vmcnt(15)
	v_pk_fma_f32 v[6:7], v[6:7], v[136:137], v[192:193]
	v_pk_fma_f32 v[4:5], v[4:5], v[134:135], v[190:191]
	global_load_dwordx4 v[190:193], v[164:165], off offset:512
	s_waitcnt vmcnt(15)
	v_pk_fma_f32 v[116:117], v[116:117], v[140:141], v[200:201]
	v_pk_fma_f32 v[114:115], v[114:115], v[138:139], v[198:199]
	v_add_co_u32_e32 v164, vcc, 0x120000, v150
	s_nop 1
	v_addc_co_u32_e32 v165, vcc, 0, v151, vcc
	global_load_dwordx4 v[198:201], v[164:165], off
	s_waitcnt vmcnt(15)
	v_pk_fma_f32 v[120:121], v[120:121], v[144:145], v[204:205]
	v_pk_fma_f32 v[118:119], v[118:119], v[142:143], v[202:203]
	global_load_dwordx4 v[202:205], v[164:165], off offset:16
	s_waitcnt vmcnt(15)
	v_pk_fma_f32 v[8:9], v[8:9], v[130:131], v[206:207]
	v_pk_fma_f32 v[10:11], v[10:11], v[132:133], v[208:209]
	global_load_dwordx4 v[206:209], v[164:165], off offset:528
	s_waitcnt vmcnt(15)
	v_pk_fma_f32 v[14:15], v[14:15], v[136:137], v[216:217]
	v_pk_fma_f32 v[12:13], v[12:13], v[134:135], v[214:215]
	global_load_dwordx4 v[214:217], v[164:165], off offset:512
	s_waitcnt vmcnt(15)
	v_pk_fma_f32 v[124:125], v[124:125], v[140:141], v[220:221]
	v_pk_fma_f32 v[122:123], v[122:123], v[138:139], v[218:219]
	v_add_co_u32_e32 v164, vcc, 0x140000, v150
	s_nop 1
	v_addc_co_u32_e32 v165, vcc, 0, v151, vcc
	global_load_dwordx4 v[218:221], v[164:165], off
	s_waitcnt vmcnt(15)
	v_pk_fma_f32 v[128:129], v[128:129], v[144:145], v[224:225]
	v_pk_fma_f32 v[126:127], v[126:127], v[142:143], v[222:223]
	global_load_dwordx4 v[222:225], v[164:165], off offset:16
	s_waitcnt vmcnt(15)
	v_pk_fma_f32 v[20:21], v[20:21], v[130:131], v[226:227]
	v_pk_fma_f32 v[22:23], v[22:23], v[132:133], v[228:229]
	global_load_dwordx4 v[226:229], v[164:165], off offset:528
	s_waitcnt vmcnt(15)
	v_pk_fma_f32 v[26:27], v[26:27], v[136:137], v[232:233]
	v_pk_fma_f32 v[24:25], v[24:25], v[134:135], v[230:231]
	global_load_dwordx4 v[230:233], v[164:165], off offset:512
	s_waitcnt vmcnt(15)
	v_pk_fma_f32 v[90:91], v[90:91], v[140:141], v[236:237]
	v_pk_fma_f32 v[88:89], v[88:89], v[138:139], v[234:235]
	v_add_co_u32_e32 v164, vcc, 0x160000, v150
	s_nop 1
	v_addc_co_u32_e32 v165, vcc, 0, v151, vcc
	global_load_dwordx4 v[234:237], v[164:165], off
	s_waitcnt vmcnt(15)
	v_pk_fma_f32 v[94:95], v[94:95], v[144:145], v[240:241]
	v_pk_fma_f32 v[92:93], v[92:93], v[142:143], v[238:239]
	global_load_dwordx4 v[238:241], v[164:165], off offset:16
	s_waitcnt vmcnt(15)
	v_pk_fma_f32 v[38:39], v[38:39], v[132:133], v[244:245]
	v_pk_fma_f32 v[36:37], v[36:37], v[130:131], v[242:243]
	global_load_dwordx4 v[242:245], v[164:165], off offset:528
	s_waitcnt vmcnt(15)
	v_pk_fma_f32 v[42:43], v[42:43], v[136:137], v[156:157]
	v_pk_fma_f32 v[40:41], v[40:41], v[134:135], v[154:155]
	global_load_dwordx4 v[154:157], v[164:165], off offset:512
	s_waitcnt vmcnt(15)
	v_pk_fma_f32 v[104:105], v[104:105], v[144:145], v[180:181]
	v_pk_fma_f32 v[102:103], v[102:103], v[142:143], v[178:179]
	s_waitcnt vmcnt(14)
	v_pk_fma_f32 v[100:101], v[100:101], v[140:141], v[184:185]
	v_pk_fma_f32 v[98:99], v[98:99], v[138:139], v[182:183]
	s_waitcnt vmcnt(13)
	v_pk_fma_f32 v[56:57], v[56:57], v[130:131], v[186:187]
	v_pk_fma_f32 v[58:59], v[58:59], v[132:133], v[188:189]
	s_waitcnt vmcnt(12)
	v_pk_fma_f32 v[62:63], v[62:63], v[136:137], v[192:193]
	v_pk_fma_f32 v[60:61], v[60:61], v[134:135], v[190:191]
	s_waitcnt vmcnt(11)
	v_pk_fma_f32 v[86:87], v[86:87], v[144:145], v[200:201]
	v_pk_fma_f32 v[84:85], v[84:85], v[142:143], v[198:199]
	s_waitcnt vmcnt(10)
	v_pk_fma_f32 v[82:83], v[82:83], v[140:141], v[204:205]
	v_pk_fma_f32 v[80:81], v[80:81], v[138:139], v[202:203]
	s_waitcnt vmcnt(9)
	v_pk_fma_f32 v[72:73], v[72:73], v[130:131], v[206:207]
	v_pk_fma_f32 v[74:75], v[74:75], v[132:133], v[208:209]
	s_waitcnt vmcnt(8)
	v_pk_fma_f32 v[78:79], v[78:79], v[136:137], v[216:217]
	v_pk_fma_f32 v[76:77], v[76:77], v[134:135], v[214:215]
	s_waitcnt vmcnt(7)
	v_pk_fma_f32 v[70:71], v[70:71], v[144:145], v[220:221]
	v_pk_fma_f32 v[68:69], v[68:69], v[142:143], v[218:219]
	s_waitcnt vmcnt(6)
	v_pk_fma_f32 v[66:67], v[66:67], v[140:141], v[224:225]
	v_pk_fma_f32 v[64:65], v[64:65], v[138:139], v[222:223]
	s_waitcnt vmcnt(5)
	v_pk_fma_f32 v[50:51], v[50:51], v[132:133], v[228:229]
	v_pk_fma_f32 v[48:49], v[48:49], v[130:131], v[226:227]
	s_waitcnt vmcnt(4)
	v_pk_fma_f32 v[54:55], v[54:55], v[136:137], v[232:233]
	v_pk_fma_f32 v[52:53], v[52:53], v[134:135], v[230:231]
	s_waitcnt vmcnt(3)
	v_pk_fma_f32 v[46:47], v[46:47], v[144:145], v[236:237]
	v_pk_fma_f32 v[44:45], v[44:45], v[142:143], v[234:235]
	s_waitcnt vmcnt(2)
	v_pk_fma_f32 v[34:35], v[34:35], v[140:141], v[240:241]
	v_pk_fma_f32 v[32:33], v[32:33], v[138:139], v[238:239]
	s_waitcnt vmcnt(1)
	v_pk_fma_f32 v[18:19], v[18:19], v[132:133], v[244:245]
	v_pk_fma_f32 v[16:17], v[16:17], v[130:131], v[242:243]
	s_waitcnt vmcnt(0)
	v_pk_fma_f32 v[28:29], v[28:29], v[134:135], v[154:155]
	v_pk_fma_f32 v[30:31], v[30:31], v[136:137], v[156:157]
	s_mov_b64 s[0:1], 0x160000
	s_branch .Lmy_pad_0
	s_nop 0
	s_nop 0
	s_nop 0
	s_nop 0
	s_nop 0
	s_nop 0
	s_nop 0
	s_nop 0
	s_nop 0
	s_nop 0
	s_nop 0
	s_nop 0
	s_nop 0
	s_nop 0
	s_nop 0
	s_nop 0
	s_nop 0
	s_nop 0
	s_nop 0
	s_nop 0
	s_nop 0
	s_nop 0
	s_nop 0
	s_nop 0
	s_nop 0
	s_nop 0
	s_nop 0
	s_nop 0
	s_nop 0
	s_nop 0
